# hand-scheduled attention inner loop (2 key tiles per iteration) for NSA-selected and MoBA items
# speedup vs baseline: 1.1059x; 1.0021x over previous
; #define MFMA32(a, b, c) __builtin_amdgcn_mfma_f32_32x32x16_bf16((a), (b), (c), 0, 0, 0)
; template <class KP, class VP, class ACT, class FILL>
; DI void attn_loop(AttnSt& st, const bf16x8 (&qf)[4], int k0, int k1, size_t vstride, KP kp, VP vp, ACT act, FILL fill) {
;   KVT cur, nxt;
;   {
;     KVT t0; load_kv(t0, kp(k0), vp(k0), vstride);
; #pragma unroll
;     for (int i = 0; i < 8; ++i) cur.v[i] = t0.v[i];
; #pragma unroll
;     for (int i = 0; i < 4; ++i) cur.k[i] = t0.k[i];
;   }
;   f32x16 s_cur;
;   { const float z = 0.f;
; #pragma unroll
;     for (int i = 0; i < 16; ++i) s_cur[i] = z; }
; #pragma unroll
;   for (int ss = 0; ss < 4; ++ss) s_cur = MFMA32(cur.k[ss], qf[ss], s_cur);
;   {
;     const int kn = (k0 < k1) ? k0 + 1 : k1;
;     const bf16_t* krow = kp(kn);
; #pragma unroll
;     for (int ss = 0; ss < 4; ++ss) nxt.k[ss] = *(const bf16x8*)(krow + 512 * ss);
;   }
; DI void moba_item(const Params& p, int b, int hd, int qb, const unsigned char* blut, const float* tbl) {
;     ...
;   const bf16_t* K = (const bf16_t*)(p.ws + OFF_KM) + (size_t)bh * 4096 * 64;
;   const bf16_t* Vt = (const bf16_t*)(p.ws + OFF_VMT) + (size_t)bh * 64 * 4096;
;   AttnSt st; attn_init(st);
;   attn_loop(st, qf, 0, qb, 32,
;     [&](int kt) { return K + (size_t)kt * 2048 + (h * 32 + r) * 8; },
;     [&](int kt) { return Vt + (size_t)kt * 2048 + (h * 32 + r) * 4; },
;     [&](int kt) { return __ballot((mmask >> (kt >> 3)) & 1u) != 0ull; },
;     [&](int kt, const f32x16& s, float (&lg)[16]) {
.LBB0_942:
	s_andn2_saveexec_b64 s[8:9], s[8:9]
	v_mov_b32_e32 v0, 0
	s_or_b64 exec, exec, s[8:9]
	v_readlane_b32 s8, v253, 49
	v_lshlrev_b32_e32 v1, 3, v18
	v_lshlrev_b64 v[14:15], 19, v[16:17]
	v_readlane_b32 s9, v253, 50
	v_lshl_or_b32 v130, v19, 8, v1
	v_lshlrev_b32_e32 v26, 1, v130
	v_lshl_add_u64 v[16:17], s[8:9], 0, v[14:15]
	v_mov_b32_e32 v27, v131
	v_lshl_add_u64 v[134:135], v[16:17], 0, v[26:27]
	global_load_dwordx4 v[2:5], v[134:135], off
	global_load_dwordx4 v[6:9], v[134:135], off offset:1024
	global_load_dwordx4 v[10:13], v[134:135], off offset:2048
	global_load_dwordx4 v[22:25], v[134:135], off offset:3072
	v_readlane_b32 s8, v253, 51
	v_cmp_eq_u32_e32 vcc, 0, v154
	v_readlane_b32 s9, v253, 52
	v_mov_b32_e32 v29, v131
	v_cndmask_b32_e64 v28, v197, 0, vcc
	v_lshl_add_u64 v[14:15], s[8:9], 0, v[14:15]
	v_lshl_add_u64 v[16:17], v[16:17], 0, v[28:29]
	v_lshl_add_u64 v[16:17], v[16:17], 0, v[26:27]
	v_lshl_add_u64 v[136:137], v[14:15], 0, v[130:131]
	global_load_dwordx4 v[108:111], v[16:17], off offset:3072
	global_load_dwordx4 v[104:107], v[16:17], off offset:2048
	global_load_dwordx4 v[100:103], v[16:17], off offset:1024
	global_load_dwordx4 v[96:99], v[16:17], off
	global_load_dwordx2 v[114:115], v[136:137], off offset:3584
	global_load_dwordx2 v[112:113], v[136:137], off offset:3072
	global_load_dwordx2 v[118:119], v[136:137], off offset:2560
	global_load_dwordx2 v[116:117], v[136:137], off offset:2048
	global_load_dwordx2 v[122:123], v[136:137], off offset:1536
	global_load_dwordx2 v[120:121], v[136:137], off offset:1024
	global_load_dwordx2 v[126:127], v[136:137], off offset:512
	global_load_dwordx2 v[124:125], v[136:137], off
	s_mov_b32 s56, 0
	v_lshrrev_b32_e32 v1, 3, v154
	s_mov_b32 s57, s56
	v_lshl_or_b32 v157, 1, v1, v0
	s_mov_b32 s58, s56
	s_mov_b32 s59, s56
	s_mov_b32 s60, s56
	s_mov_b32 s61, s56
	s_mov_b32 s62, s56
	s_mov_b32 s63, s56
	s_mov_b32 s64, s56
	s_mov_b32 s65, s56
	s_mov_b32 s66, s56
	s_mov_b32 s67, s56
	s_mov_b32 s68, s56
	s_mov_b32 s69, s56
	s_mov_b32 s70, s56
	s_mov_b32 s71, s56
	v_sub_u32_e32 v16, 0, v21
	v_lshlrev_b32_e32 v155, 2, v19
	v_lshlrev_b32_e32 v133, 6, v20
	v_lshl_add_u32 v156, v20, 7, 0
	v_sub_u32_e32 v158, v18, v155
	v_lshl_add_u32 v159, v16, 5, v208
	v_mov_b32_e32 v160, 0
	v_mov_b32_e32 v161, 0xff800000
	s_waitcnt vmcnt(15)
	v_mfma_f32_32x32x16_bf16 v[48:63], v[2:5], v[80:83], 0
	s_waitcnt vmcnt(14)
	v_mfma_f32_32x32x16_bf16 v[48:63], v[6:9], v[84:87], v[48:63]
	s_waitcnt vmcnt(13)
	v_mfma_f32_32x32x16_bf16 v[48:63], v[10:13], v[88:91], v[48:63]
	v_mov_b64_e32 v[0:1], s[56:57]
	v_mov_b64_e32 v[14:15], s[70:71]
	v_mov_b64_e32 v[2:3], s[58:59]
	v_mov_b64_e32 v[4:5], s[60:61]
	v_mov_b64_e32 v[6:7], s[62:63]
	v_mov_b64_e32 v[8:9], s[64:65]
	v_mov_b64_e32 v[10:11], s[66:67]
	s_waitcnt vmcnt(12)
	v_mfma_f32_32x32x16_bf16 v[48:63], v[22:25], v[92:95], v[48:63]
	v_mov_b64_e32 v[12:13], s[68:69]
	v_mov_b64_e32 v[30:31], v[14:15]
	s_mov_b64 s[58:59], 0
	v_mov_b64_e32 v[28:29], v[12:13]
	v_mov_b64_e32 v[26:27], v[10:11]
	v_mov_b64_e32 v[24:25], v[8:9]
	v_mov_b64_e32 v[22:23], v[6:7]
	v_mov_b64_e32 v[20:21], v[4:5]
	v_mov_b64_e32 v[18:19], v[2:3]
	v_mov_b64_e32 v[16:17], v[0:1]
	s_waitcnt vmcnt(0)
	v_readfirstlane_b32 s60, v154
	ds_read_b32 v178, v156 offset:4988
	s_mov_b32 s56, 0
	s_mov_b32 s23, 0
	s_min_u32 s24, s23, s60
	s_lshl_b32 s26, s24, 12
	s_mov_b32 s27, 0
	v_lshl_add_u64 v[186:187], v[134:135], 0, s[26:27]
	global_load_dwordx4 v[96:99], v[186:187], off
	global_load_dwordx4 v[100:103], v[186:187], off offset:1024
	global_load_dwordx4 v[104:107], v[186:187], off offset:2048
	global_load_dwordx4 v[108:111], v[186:187], off offset:3072
	s_mov_b32 s23, 1
	s_min_u32 s24, s23, s60
	s_lshl_b32 s26, s24, 12
	s_mov_b32 s27, 0
	v_lshl_add_u64 v[186:187], v[134:135], 0, s[26:27]
	global_load_dwordx4 v[112:115], v[186:187], off
	global_load_dwordx4 v[116:119], v[186:187], off offset:1024
	global_load_dwordx4 v[120:123], v[186:187], off offset:2048
	global_load_dwordx4 v[124:127], v[186:187], off offset:3072
	s_mov_b32 s23, 0
	s_min_u32 s24, s23, s60
	s_lshl_b32 s26, s24, 12
	s_mov_b32 s27, 0
	v_lshl_add_u64 v[218:219], v[136:137], 0, s[26:27]
	global_load_dwordx2 v[64:65], v[218:219], off
	global_load_dwordx2 v[66:67], v[218:219], off offset:512
	global_load_dwordx2 v[68:69], v[218:219], off offset:1024
	global_load_dwordx2 v[70:71], v[218:219], off offset:1536
	global_load_dwordx2 v[72:73], v[218:219], off offset:2048
	global_load_dwordx2 v[74:75], v[218:219], off offset:2560
	global_load_dwordx2 v[76:77], v[218:219], off offset:3072
	global_load_dwordx2 v[78:79], v[218:219], off offset:3584
	s_mov_b32 s23, 1
	s_min_u32 s24, s23, s60
	s_lshl_b32 s26, s24, 12
	s_mov_b32 s27, 0
	v_lshl_add_u64 v[218:219], v[136:137], 0, s[26:27]
	global_load_dwordx2 v[138:139], v[218:219], off
	global_load_dwordx2 v[140:141], v[218:219], off offset:512
	global_load_dwordx2 v[142:143], v[218:219], off offset:1024
	global_load_dwordx2 v[144:145], v[218:219], off offset:1536
	global_load_dwordx2 v[146:147], v[218:219], off offset:2048
	global_load_dwordx2 v[148:149], v[218:219], off offset:2560
	global_load_dwordx2 v[150:151], v[218:219], off offset:3072
	global_load_dwordx2 v[152:153], v[218:219], off offset:3584
	s_waitcnt lgkmcnt(0)
; #define NEGINF (-__builtin_inff())
; DI int crow(int i, int h) { return (i & 3) + 8 * (i >> 2) + 4 * h; }
; DI void bias16(const unsigned char* blut, const float* tblh, const int (&dist)[16], float (&bv)[16]) {
;   int bk[16];
; #pragma unroll
;   for (int i = 0; i < 16; ++i) { const int d = dist[i] < 0 ? 0 : (dist[i] > 2048 ? 2048 : dist[i]); bk[i] = blut[d]; }
; #pragma unroll
;   for (int i = 0; i < 16; ++i) asm volatile("" : "+v"(bk[i]));
; #pragma unroll
;   for (int i = 0; i < 16; ++i) bv[i] = tblh[bk[i]];
; #pragma unroll
;   for (int i = 0; i < 16; ++i) asm volatile("" : "+v"(bv[i]));
; }
; DI void moba_item(const Params& p, int b, int hd, int qb, const unsigned char* blut, const float* tbl) {
;     ...
;     [&](int kt, const f32x16& s, float (&lg)[16]) {
;       const bool bs = (mmask >> (kt >> 3)) & 1u;
;       if (qb * 32 - (kt * 32 + 31) >= 1513) {
;         const float b31 = tblh[31];
; #pragma unroll
;         for (int i = 0; i < 16; ++i) lg[i] = bs ? s[i] + b31 : NEGINF;
;       } else {
;         int dist[16]; float bv[16];
; #pragma unroll
;         for (int i = 0; i < 16; ++i) dist[i] = t - (kt * 32 + crow(i, h));
;         bias16(blut, tblh, dist, bv);
; #pragma unroll
;         for (int i = 0; i < 16; ++i) lg[i] = (bs && dist[i] >= 0) ? s[i] + bv[i] : NEGINF;
;       }
.Lamoba_loop:
	s_waitcnt vmcnt(16)
	v_mfma_f32_32x32x16_bf16 v[32:47], v[96:99], v[80:83], 0
	v_mfma_f32_32x32x16_bf16 v[48:63], v[112:115], v[80:83], 0
	v_mfma_f32_32x32x16_bf16 v[32:47], v[100:103], v[84:87], v[32:47]
	v_mfma_f32_32x32x16_bf16 v[48:63], v[116:119], v[84:87], v[48:63]
	v_mfma_f32_32x32x16_bf16 v[32:47], v[104:107], v[88:91], v[32:47]
	v_mfma_f32_32x32x16_bf16 v[48:63], v[120:123], v[88:91], v[48:63]
	v_mfma_f32_32x32x16_bf16 v[32:47], v[108:111], v[92:95], v[32:47]
	v_mfma_f32_32x32x16_bf16 v[48:63], v[124:127], v[92:95], v[48:63]
	s_add_u32 s23, s56, 2
	s_min_u32 s24, s23, s60
	s_lshl_b32 s26, s24, 12
	s_mov_b32 s27, 0
	v_lshl_add_u64 v[186:187], v[134:135], 0, s[26:27]
	global_load_dwordx4 v[96:99], v[186:187], off
	global_load_dwordx4 v[100:103], v[186:187], off offset:1024
	global_load_dwordx4 v[104:107], v[186:187], off offset:2048
	global_load_dwordx4 v[108:111], v[186:187], off offset:3072
	s_add_u32 s23, s56, 3
	s_min_u32 s24, s23, s60
	s_lshl_b32 s26, s24, 12
	s_mov_b32 s27, 0
	v_lshl_add_u64 v[186:187], v[134:135], 0, s[26:27]
	global_load_dwordx4 v[112:115], v[186:187], off
	global_load_dwordx4 v[116:119], v[186:187], off offset:1024
	global_load_dwordx4 v[120:123], v[186:187], off offset:2048
	global_load_dwordx4 v[124:127], v[186:187], off offset:3072
	s_sub_i32 s61, s60, s56
	s_lshr_b32 s23, s56, 3
	v_bfe_u32 v181, v157, s23, 1
	v_cmp_eq_u32_e64 s[62:63], 1, v181
	s_cmp_ge_i32 s61, 50
	s_cbranch_scc1 .Lamoba_far
	s_lshl_b32 s23, s61, 5
	v_add_u32_e32 v179, s23, v158
	v_subrev_u32_e32 v180, 32, v179
	s_cmp_ge_i32 s61, 2
	s_cbranch_scc1 .Lamoba_near_nodiag
	v_subrev_u32_e32 v162, 0, v179
	v_subrev_u32_e32 v163, 1, v179
	v_subrev_u32_e32 v164, 2, v179
	v_subrev_u32_e32 v165, 3, v179
	v_subrev_u32_e32 v166, 8, v179
	v_subrev_u32_e32 v167, 9, v179
	v_subrev_u32_e32 v168, 10, v179
	v_subrev_u32_e32 v169, 11, v179
	v_subrev_u32_e32 v170, 16, v179
	v_subrev_u32_e32 v171, 17, v179
	v_subrev_u32_e32 v172, 18, v179
	v_subrev_u32_e32 v173, 19, v179
	v_subrev_u32_e32 v174, 24, v179
	v_subrev_u32_e32 v175, 25, v179
	v_subrev_u32_e32 v176, 26, v179
	v_subrev_u32_e32 v177, 27, v179
	v_med3_i32 v162, v162, 0, v198
	v_med3_i32 v163, v163, 0, v198
	v_med3_i32 v164, v164, 0, v198
	v_med3_i32 v165, v165, 0, v198
	v_med3_i32 v166, v166, 0, v198
	v_med3_i32 v167, v167, 0, v198
	v_med3_i32 v168, v168, 0, v198
	v_med3_i32 v169, v169, 0, v198
	v_med3_i32 v170, v170, 0, v198
	v_med3_i32 v171, v171, 0, v198
	v_med3_i32 v172, v172, 0, v198
	v_med3_i32 v173, v173, 0, v198
	v_med3_i32 v174, v174, 0, v198
	v_med3_i32 v175, v175, 0, v198
	v_med3_i32 v176, v176, 0, v198
	v_med3_i32 v177, v177, 0, v198
	ds_read_u8 v162, v162
	ds_read_u8 v163, v163
	ds_read_u8 v164, v164
	ds_read_u8 v165, v165
	ds_read_u8 v166, v166
	ds_read_u8 v167, v167
	ds_read_u8 v168, v168
	ds_read_u8 v169, v169
	ds_read_u8 v170, v170
	ds_read_u8 v171, v171
	ds_read_u8 v172, v172
	ds_read_u8 v173, v173
	ds_read_u8 v174, v174
	ds_read_u8 v175, v175
	ds_read_u8 v176, v176
	ds_read_u8 v177, v177
	s_waitcnt lgkmcnt(15)
	v_lshl_add_u32 v162, v162, 2, v156
	s_waitcnt lgkmcnt(14)
	v_lshl_add_u32 v163, v163, 2, v156
	s_waitcnt lgkmcnt(13)
	v_lshl_add_u32 v164, v164, 2, v156
	s_waitcnt lgkmcnt(12)
	v_lshl_add_u32 v165, v165, 2, v156
	s_waitcnt lgkmcnt(11)
	v_lshl_add_u32 v166, v166, 2, v156
	s_waitcnt lgkmcnt(10)
	v_lshl_add_u32 v167, v167, 2, v156
	s_waitcnt lgkmcnt(9)
	v_lshl_add_u32 v168, v168, 2, v156
	s_waitcnt lgkmcnt(8)
	v_lshl_add_u32 v169, v169, 2, v156
	s_waitcnt lgkmcnt(7)
	v_lshl_add_u32 v170, v170, 2, v156
	s_waitcnt lgkmcnt(6)
	v_lshl_add_u32 v171, v171, 2, v156
	s_waitcnt lgkmcnt(5)
	v_lshl_add_u32 v172, v172, 2, v156
	s_waitcnt lgkmcnt(4)
	v_lshl_add_u32 v173, v173, 2, v156
	s_waitcnt lgkmcnt(3)
	v_lshl_add_u32 v174, v174, 2, v156
	s_waitcnt lgkmcnt(2)
	v_lshl_add_u32 v175, v175, 2, v156
	s_waitcnt lgkmcnt(1)
	v_lshl_add_u32 v176, v176, 2, v156
	s_waitcnt lgkmcnt(0)
	v_lshl_add_u32 v177, v177, 2, v156
	ds_read_b32 v162, v162 offset:4864
	ds_read_b32 v163, v163 offset:4864
	ds_read_b32 v164, v164 offset:4864
	ds_read_b32 v165, v165 offset:4864
	ds_read_b32 v166, v166 offset:4864
	ds_read_b32 v167, v167 offset:4864
	ds_read_b32 v168, v168 offset:4864
	ds_read_b32 v169, v169 offset:4864
	ds_read_b32 v170, v170 offset:4864
	ds_read_b32 v171, v171 offset:4864
	ds_read_b32 v172, v172 offset:4864
	ds_read_b32 v173, v173 offset:4864
	ds_read_b32 v174, v174 offset:4864
	ds_read_b32 v175, v175 offset:4864
	ds_read_b32 v176, v176 offset:4864
	ds_read_b32 v177, v177 offset:4864
	s_waitcnt lgkmcnt(15)
	v_add_f32_e32 v32, v32, v162
	v_cmp_le_i32_e32 vcc, 0, v179
	s_and_b64 vcc, vcc, s[62:63]
	v_cndmask_b32_e32 v32, v199, v32, vcc
	s_waitcnt lgkmcnt(14)
	v_add_f32_e32 v33, v33, v163
	v_cmp_le_i32_e32 vcc, 1, v179
	s_and_b64 vcc, vcc, s[62:63]
	v_cndmask_b32_e32 v33, v199, v33, vcc
	s_waitcnt lgkmcnt(13)
	v_add_f32_e32 v34, v34, v164
	v_cmp_le_i32_e32 vcc, 2, v179
	s_and_b64 vcc, vcc, s[62:63]
	v_cndmask_b32_e32 v34, v199, v34, vcc
	s_waitcnt lgkmcnt(12)
	v_add_f32_e32 v35, v35, v165
	v_cmp_le_i32_e32 vcc, 3, v179
	s_and_b64 vcc, vcc, s[62:63]
	v_cndmask_b32_e32 v35, v199, v35, vcc
	s_waitcnt lgkmcnt(11)
	v_add_f32_e32 v36, v36, v166
	v_cmp_le_i32_e32 vcc, 8, v179
	s_and_b64 vcc, vcc, s[62:63]
	v_cndmask_b32_e32 v36, v199, v36, vcc
	s_waitcnt lgkmcnt(10)
	v_add_f32_e32 v37, v37, v167
	v_cmp_le_i32_e32 vcc, 9, v179
	s_and_b64 vcc, vcc, s[62:63]
	v_cndmask_b32_e32 v37, v199, v37, vcc
	s_waitcnt lgkmcnt(9)
	v_add_f32_e32 v38, v38, v168
	v_cmp_le_i32_e32 vcc, 10, v179
	s_and_b64 vcc, vcc, s[62:63]
	v_cndmask_b32_e32 v38, v199, v38, vcc
	s_waitcnt lgkmcnt(8)
; #define NEGINF (-__builtin_inff())
; DI int crow(int i, int h) { return (i & 3) + 8 * (i >> 2) + 4 * h; }
; DI void bias16(const unsigned char* blut, const float* tblh, const int (&dist)[16], float (&bv)[16]) {
;   int bk[16];
; #pragma unroll
;   for (int i = 0; i < 16; ++i) { const int d = dist[i] < 0 ? 0 : (dist[i] > 2048 ? 2048 : dist[i]); bk[i] = blut[d]; }
; #pragma unroll
;   for (int i = 0; i < 16; ++i) asm volatile("" : "+v"(bk[i]));
; #pragma unroll
;   for (int i = 0; i < 16; ++i) bv[i] = tblh[bk[i]];
; #pragma unroll
;   for (int i = 0; i < 16; ++i) asm volatile("" : "+v"(bv[i]));
; }
; DI void moba_item(const Params& p, int b, int hd, int qb, const unsigned char* blut, const float* tbl) {
;     ...
;         int dist[16]; float bv[16];
; #pragma unroll
;         for (int i = 0; i < 16; ++i) dist[i] = t - (kt * 32 + crow(i, h));
;         bias16(blut, tblh, dist, bv);
; #pragma unroll
;         for (int i = 0; i < 16; ++i) lg[i] = (bs && dist[i] >= 0) ? s[i] + bv[i] : NEGINF;
	v_add_f32_e32 v39, v39, v169
	v_cmp_le_i32_e32 vcc, 11, v179
	s_and_b64 vcc, vcc, s[62:63]
	v_cndmask_b32_e32 v39, v199, v39, vcc
	s_waitcnt lgkmcnt(7)
	v_add_f32_e32 v40, v40, v170
	v_cmp_le_i32_e32 vcc, 16, v179
	s_and_b64 vcc, vcc, s[62:63]
	v_cndmask_b32_e32 v40, v199, v40, vcc
	s_waitcnt lgkmcnt(6)
	v_add_f32_e32 v41, v41, v171
	v_cmp_le_i32_e32 vcc, 17, v179
	s_and_b64 vcc, vcc, s[62:63]
	v_cndmask_b32_e32 v41, v199, v41, vcc
	s_waitcnt lgkmcnt(5)
	v_add_f32_e32 v42, v42, v172
	v_cmp_le_i32_e32 vcc, 18, v179
	s_and_b64 vcc, vcc, s[62:63]
	v_cndmask_b32_e32 v42, v199, v42, vcc
	s_waitcnt lgkmcnt(4)
	v_add_f32_e32 v43, v43, v173
	v_cmp_le_i32_e32 vcc, 19, v179
	s_and_b64 vcc, vcc, s[62:63]
	v_cndmask_b32_e32 v43, v199, v43, vcc
	s_waitcnt lgkmcnt(3)
	v_add_f32_e32 v44, v44, v174
	v_cmp_le_i32_e32 vcc, 24, v179
	s_and_b64 vcc, vcc, s[62:63]
	v_cndmask_b32_e32 v44, v199, v44, vcc
	s_waitcnt lgkmcnt(2)
	v_add_f32_e32 v45, v45, v175
	v_cmp_le_i32_e32 vcc, 25, v179
	s_and_b64 vcc, vcc, s[62:63]
	v_cndmask_b32_e32 v45, v199, v45, vcc
	s_waitcnt lgkmcnt(1)
	v_add_f32_e32 v46, v46, v176
	v_cmp_le_i32_e32 vcc, 26, v179
	s_and_b64 vcc, vcc, s[62:63]
	v_cndmask_b32_e32 v46, v199, v46, vcc
	s_waitcnt lgkmcnt(0)
	v_add_f32_e32 v47, v47, v177
	v_cmp_le_i32_e32 vcc, 27, v179
	s_and_b64 vcc, vcc, s[62:63]
	v_cndmask_b32_e32 v47, v199, v47, vcc
	v_subrev_u32_e32 v162, 0, v180
	v_subrev_u32_e32 v163, 1, v180
	v_subrev_u32_e32 v164, 2, v180
	v_subrev_u32_e32 v165, 3, v180
	v_subrev_u32_e32 v166, 8, v180
	v_subrev_u32_e32 v167, 9, v180
	v_subrev_u32_e32 v168, 10, v180
	v_subrev_u32_e32 v169, 11, v180
	v_subrev_u32_e32 v170, 16, v180
	v_subrev_u32_e32 v171, 17, v180
	v_subrev_u32_e32 v172, 18, v180
	v_subrev_u32_e32 v173, 19, v180
	v_subrev_u32_e32 v174, 24, v180
	v_subrev_u32_e32 v175, 25, v180
	v_subrev_u32_e32 v176, 26, v180
	v_subrev_u32_e32 v177, 27, v180
	v_med3_i32 v162, v162, 0, v198
	v_med3_i32 v163, v163, 0, v198
	v_med3_i32 v164, v164, 0, v198
	v_med3_i32 v165, v165, 0, v198
	v_med3_i32 v166, v166, 0, v198
	v_med3_i32 v167, v167, 0, v198
	v_med3_i32 v168, v168, 0, v198
	v_med3_i32 v169, v169, 0, v198
	v_med3_i32 v170, v170, 0, v198
	v_med3_i32 v171, v171, 0, v198
	v_med3_i32 v172, v172, 0, v198
	v_med3_i32 v173, v173, 0, v198
	v_med3_i32 v174, v174, 0, v198
	v_med3_i32 v175, v175, 0, v198
	v_med3_i32 v176, v176, 0, v198
	v_med3_i32 v177, v177, 0, v198
	ds_read_u8 v162, v162
	ds_read_u8 v163, v163
	ds_read_u8 v164, v164
	ds_read_u8 v165, v165
	ds_read_u8 v166, v166
	ds_read_u8 v167, v167
	ds_read_u8 v168, v168
	ds_read_u8 v169, v169
	ds_read_u8 v170, v170
	ds_read_u8 v171, v171
	ds_read_u8 v172, v172
	ds_read_u8 v173, v173
	ds_read_u8 v174, v174
	ds_read_u8 v175, v175
	ds_read_u8 v176, v176
	ds_read_u8 v177, v177
	s_waitcnt lgkmcnt(15)
	v_lshl_add_u32 v162, v162, 2, v156
	s_waitcnt lgkmcnt(14)
	v_lshl_add_u32 v163, v163, 2, v156
	s_waitcnt lgkmcnt(13)
	v_lshl_add_u32 v164, v164, 2, v156
	s_waitcnt lgkmcnt(12)
	v_lshl_add_u32 v165, v165, 2, v156
	s_waitcnt lgkmcnt(11)
	v_lshl_add_u32 v166, v166, 2, v156
	s_waitcnt lgkmcnt(10)
	v_lshl_add_u32 v167, v167, 2, v156
	s_waitcnt lgkmcnt(9)
	v_lshl_add_u32 v168, v168, 2, v156
	s_waitcnt lgkmcnt(8)
	v_lshl_add_u32 v169, v169, 2, v156
	s_waitcnt lgkmcnt(7)
	v_lshl_add_u32 v170, v170, 2, v156
	s_waitcnt lgkmcnt(6)
	v_lshl_add_u32 v171, v171, 2, v156
	s_waitcnt lgkmcnt(5)
	v_lshl_add_u32 v172, v172, 2, v156
	s_waitcnt lgkmcnt(4)
	v_lshl_add_u32 v173, v173, 2, v156
	s_waitcnt lgkmcnt(3)
	v_lshl_add_u32 v174, v174, 2, v156
	s_waitcnt lgkmcnt(2)
	v_lshl_add_u32 v175, v175, 2, v156
	s_waitcnt lgkmcnt(1)
	v_lshl_add_u32 v176, v176, 2, v156
	s_waitcnt lgkmcnt(0)
	v_lshl_add_u32 v177, v177, 2, v156
	ds_read_b32 v162, v162 offset:4864
	ds_read_b32 v163, v163 offset:4864
	ds_read_b32 v164, v164 offset:4864
	ds_read_b32 v165, v165 offset:4864
	ds_read_b32 v166, v166 offset:4864
	ds_read_b32 v167, v167 offset:4864
	ds_read_b32 v168, v168 offset:4864
	ds_read_b32 v169, v169 offset:4864
	ds_read_b32 v170, v170 offset:4864
	ds_read_b32 v171, v171 offset:4864
	ds_read_b32 v172, v172 offset:4864
	ds_read_b32 v173, v173 offset:4864
	ds_read_b32 v174, v174 offset:4864
	ds_read_b32 v175, v175 offset:4864
	ds_read_b32 v176, v176 offset:4864
	ds_read_b32 v177, v177 offset:4864
	s_waitcnt lgkmcnt(15)
	v_add_f32_e32 v48, v48, v162
	v_cmp_le_i32_e32 vcc, 0, v180
	s_and_b64 vcc, vcc, s[62:63]
	v_cndmask_b32_e32 v48, v199, v48, vcc
	s_waitcnt lgkmcnt(14)
	v_add_f32_e32 v49, v49, v163
	v_cmp_le_i32_e32 vcc, 1, v180
	s_and_b64 vcc, vcc, s[62:63]
	v_cndmask_b32_e32 v49, v199, v49, vcc
	s_waitcnt lgkmcnt(13)
	v_add_f32_e32 v50, v50, v164
	v_cmp_le_i32_e32 vcc, 2, v180
	s_and_b64 vcc, vcc, s[62:63]
	v_cndmask_b32_e32 v50, v199, v50, vcc
	s_waitcnt lgkmcnt(12)
	v_add_f32_e32 v51, v51, v165
	v_cmp_le_i32_e32 vcc, 3, v180
	s_and_b64 vcc, vcc, s[62:63]
	v_cndmask_b32_e32 v51, v199, v51, vcc
	s_waitcnt lgkmcnt(11)
	v_add_f32_e32 v52, v52, v166
	v_cmp_le_i32_e32 vcc, 8, v180
	s_and_b64 vcc, vcc, s[62:63]
	v_cndmask_b32_e32 v52, v199, v52, vcc
	s_waitcnt lgkmcnt(10)
	v_add_f32_e32 v53, v53, v167
	v_cmp_le_i32_e32 vcc, 9, v180
	s_and_b64 vcc, vcc, s[62:63]
	v_cndmask_b32_e32 v53, v199, v53, vcc
	s_waitcnt lgkmcnt(9)
	v_add_f32_e32 v54, v54, v168
	v_cmp_le_i32_e32 vcc, 10, v180
	s_and_b64 vcc, vcc, s[62:63]
	v_cndmask_b32_e32 v54, v199, v54, vcc
	s_waitcnt lgkmcnt(8)
	v_add_f32_e32 v55, v55, v169
	v_cmp_le_i32_e32 vcc, 11, v180
	s_and_b64 vcc, vcc, s[62:63]
	v_cndmask_b32_e32 v55, v199, v55, vcc
	s_waitcnt lgkmcnt(7)
	v_add_f32_e32 v56, v56, v170
	v_cmp_le_i32_e32 vcc, 16, v180
	s_and_b64 vcc, vcc, s[62:63]
	v_cndmask_b32_e32 v56, v199, v56, vcc
	s_waitcnt lgkmcnt(6)
	v_add_f32_e32 v57, v57, v171
	v_cmp_le_i32_e32 vcc, 17, v180
	s_and_b64 vcc, vcc, s[62:63]
	v_cndmask_b32_e32 v57, v199, v57, vcc
	s_waitcnt lgkmcnt(5)
	v_add_f32_e32 v58, v58, v172
	v_cmp_le_i32_e32 vcc, 18, v180
	s_and_b64 vcc, vcc, s[62:63]
	v_cndmask_b32_e32 v58, v199, v58, vcc
	s_waitcnt lgkmcnt(4)
	v_add_f32_e32 v59, v59, v173
	v_cmp_le_i32_e32 vcc, 19, v180
	s_and_b64 vcc, vcc, s[62:63]
	v_cndmask_b32_e32 v59, v199, v59, vcc
	s_waitcnt lgkmcnt(3)
	v_add_f32_e32 v60, v60, v174
	v_cmp_le_i32_e32 vcc, 24, v180
	s_and_b64 vcc, vcc, s[62:63]
	v_cndmask_b32_e32 v60, v199, v60, vcc
	s_waitcnt lgkmcnt(2)
	v_add_f32_e32 v61, v61, v175
	v_cmp_le_i32_e32 vcc, 25, v180
	s_and_b64 vcc, vcc, s[62:63]
	v_cndmask_b32_e32 v61, v199, v61, vcc
	s_waitcnt lgkmcnt(1)
	v_add_f32_e32 v62, v62, v176
	v_cmp_le_i32_e32 vcc, 26, v180
	s_and_b64 vcc, vcc, s[62:63]
	v_cndmask_b32_e32 v62, v199, v62, vcc
	s_waitcnt lgkmcnt(0)
	v_add_f32_e32 v63, v63, v177
	v_cmp_le_i32_e32 vcc, 27, v180
	s_and_b64 vcc, vcc, s[62:63]
	v_cndmask_b32_e32 v63, v199, v63, vcc
	s_branch .Lamoba_softmax
; #define NEGINF (-__builtin_inff())
; DI int crow(int i, int h) { return (i & 3) + 8 * (i >> 2) + 4 * h; }
; DI void bias16(const unsigned char* blut, const float* tblh, const int (&dist)[16], float (&bv)[16]) {
;   int bk[16];
; #pragma unroll
;   for (int i = 0; i < 16; ++i) { const int d = dist[i] < 0 ? 0 : (dist[i] > 2048 ? 2048 : dist[i]); bk[i] = blut[d]; }
; #pragma unroll
;   for (int i = 0; i < 16; ++i) asm volatile("" : "+v"(bk[i]));
; #pragma unroll
;   for (int i = 0; i < 16; ++i) bv[i] = tblh[bk[i]];
; #pragma unroll
;   for (int i = 0; i < 16; ++i) asm volatile("" : "+v"(bv[i]));
; }
; DI void moba_item(const Params& p, int b, int hd, int qb, const unsigned char* blut, const float* tbl) {
;     ...
;         int dist[16]; float bv[16];
; #pragma unroll
;         for (int i = 0; i < 16; ++i) dist[i] = t - (kt * 32 + crow(i, h));
;         bias16(blut, tblh, dist, bv);
; #pragma unroll
;         for (int i = 0; i < 16; ++i) lg[i] = (bs && dist[i] >= 0) ? s[i] + bv[i] : NEGINF;
.Lamoba_near_nodiag:
	v_subrev_u32_e32 v162, 0, v179
	v_subrev_u32_e32 v163, 1, v179
	v_subrev_u32_e32 v164, 2, v179
	v_subrev_u32_e32 v165, 3, v179
	v_subrev_u32_e32 v166, 8, v179
	v_subrev_u32_e32 v167, 9, v179
	v_subrev_u32_e32 v168, 10, v179
	v_subrev_u32_e32 v169, 11, v179
	v_subrev_u32_e32 v170, 16, v179
	v_subrev_u32_e32 v171, 17, v179
	v_subrev_u32_e32 v172, 18, v179
	v_subrev_u32_e32 v173, 19, v179
	v_subrev_u32_e32 v174, 24, v179
	v_subrev_u32_e32 v175, 25, v179
	v_subrev_u32_e32 v176, 26, v179
	v_subrev_u32_e32 v177, 27, v179
	v_med3_i32 v162, v162, 0, v198
	v_med3_i32 v163, v163, 0, v198
	v_med3_i32 v164, v164, 0, v198
	v_med3_i32 v165, v165, 0, v198
	v_med3_i32 v166, v166, 0, v198
	v_med3_i32 v167, v167, 0, v198
	v_med3_i32 v168, v168, 0, v198
	v_med3_i32 v169, v169, 0, v198
	v_med3_i32 v170, v170, 0, v198
	v_med3_i32 v171, v171, 0, v198
	v_med3_i32 v172, v172, 0, v198
	v_med3_i32 v173, v173, 0, v198
	v_med3_i32 v174, v174, 0, v198
	v_med3_i32 v175, v175, 0, v198
	v_med3_i32 v176, v176, 0, v198
	v_med3_i32 v177, v177, 0, v198
	ds_read_u8 v162, v162
	ds_read_u8 v163, v163
	ds_read_u8 v164, v164
	ds_read_u8 v165, v165
	ds_read_u8 v166, v166
	ds_read_u8 v167, v167
	ds_read_u8 v168, v168
	ds_read_u8 v169, v169
	ds_read_u8 v170, v170
	ds_read_u8 v171, v171
	ds_read_u8 v172, v172
	ds_read_u8 v173, v173
	ds_read_u8 v174, v174
	ds_read_u8 v175, v175
	ds_read_u8 v176, v176
	ds_read_u8 v177, v177
	s_waitcnt lgkmcnt(15)
	v_lshl_add_u32 v162, v162, 2, v156
	s_waitcnt lgkmcnt(14)
	v_lshl_add_u32 v163, v163, 2, v156
	s_waitcnt lgkmcnt(13)
	v_lshl_add_u32 v164, v164, 2, v156
	s_waitcnt lgkmcnt(12)
	v_lshl_add_u32 v165, v165, 2, v156
	s_waitcnt lgkmcnt(11)
	v_lshl_add_u32 v166, v166, 2, v156
	s_waitcnt lgkmcnt(10)
	v_lshl_add_u32 v167, v167, 2, v156
	s_waitcnt lgkmcnt(9)
	v_lshl_add_u32 v168, v168, 2, v156
	s_waitcnt lgkmcnt(8)
	v_lshl_add_u32 v169, v169, 2, v156
	s_waitcnt lgkmcnt(7)
	v_lshl_add_u32 v170, v170, 2, v156
	s_waitcnt lgkmcnt(6)
	v_lshl_add_u32 v171, v171, 2, v156
	s_waitcnt lgkmcnt(5)
	v_lshl_add_u32 v172, v172, 2, v156
	s_waitcnt lgkmcnt(4)
	v_lshl_add_u32 v173, v173, 2, v156
	s_waitcnt lgkmcnt(3)
	v_lshl_add_u32 v174, v174, 2, v156
	s_waitcnt lgkmcnt(2)
	v_lshl_add_u32 v175, v175, 2, v156
	s_waitcnt lgkmcnt(1)
	v_lshl_add_u32 v176, v176, 2, v156
	s_waitcnt lgkmcnt(0)
	v_lshl_add_u32 v177, v177, 2, v156
	ds_read_b32 v162, v162 offset:4864
	ds_read_b32 v163, v163 offset:4864
	ds_read_b32 v164, v164 offset:4864
	ds_read_b32 v165, v165 offset:4864
	ds_read_b32 v166, v166 offset:4864
	ds_read_b32 v167, v167 offset:4864
	ds_read_b32 v168, v168 offset:4864
	ds_read_b32 v169, v169 offset:4864
	ds_read_b32 v170, v170 offset:4864
	ds_read_b32 v171, v171 offset:4864
	ds_read_b32 v172, v172 offset:4864
	ds_read_b32 v173, v173 offset:4864
	ds_read_b32 v174, v174 offset:4864
	ds_read_b32 v175, v175 offset:4864
	ds_read_b32 v176, v176 offset:4864
	ds_read_b32 v177, v177 offset:4864
	s_waitcnt lgkmcnt(15)
	v_add_f32_e32 v32, v32, v162
	v_cndmask_b32_e64 v32, v199, v32, s[62:63]
	s_waitcnt lgkmcnt(14)
	v_add_f32_e32 v33, v33, v163
	v_cndmask_b32_e64 v33, v199, v33, s[62:63]
	s_waitcnt lgkmcnt(13)
	v_add_f32_e32 v34, v34, v164
	v_cndmask_b32_e64 v34, v199, v34, s[62:63]
	s_waitcnt lgkmcnt(12)
	v_add_f32_e32 v35, v35, v165
	v_cndmask_b32_e64 v35, v199, v35, s[62:63]
	s_waitcnt lgkmcnt(11)
	v_add_f32_e32 v36, v36, v166
	v_cndmask_b32_e64 v36, v199, v36, s[62:63]
	s_waitcnt lgkmcnt(10)
	v_add_f32_e32 v37, v37, v167
	v_cndmask_b32_e64 v37, v199, v37, s[62:63]
	s_waitcnt lgkmcnt(9)
	v_add_f32_e32 v38, v38, v168
	v_cndmask_b32_e64 v38, v199, v38, s[62:63]
	s_waitcnt lgkmcnt(8)
	v_add_f32_e32 v39, v39, v169
	v_cndmask_b32_e64 v39, v199, v39, s[62:63]
	s_waitcnt lgkmcnt(7)
	v_add_f32_e32 v40, v40, v170
	v_cndmask_b32_e64 v40, v199, v40, s[62:63]
	s_waitcnt lgkmcnt(6)
	v_add_f32_e32 v41, v41, v171
	v_cndmask_b32_e64 v41, v199, v41, s[62:63]
	s_waitcnt lgkmcnt(5)
	v_add_f32_e32 v42, v42, v172
	v_cndmask_b32_e64 v42, v199, v42, s[62:63]
	s_waitcnt lgkmcnt(4)
	v_add_f32_e32 v43, v43, v173
	v_cndmask_b32_e64 v43, v199, v43, s[62:63]
	s_waitcnt lgkmcnt(3)
	v_add_f32_e32 v44, v44, v174
	v_cndmask_b32_e64 v44, v199, v44, s[62:63]
	s_waitcnt lgkmcnt(2)
	v_add_f32_e32 v45, v45, v175
	v_cndmask_b32_e64 v45, v199, v45, s[62:63]
	s_waitcnt lgkmcnt(1)
	v_add_f32_e32 v46, v46, v176
	v_cndmask_b32_e64 v46, v199, v46, s[62:63]
	s_waitcnt lgkmcnt(0)
	v_add_f32_e32 v47, v47, v177
	v_cndmask_b32_e64 v47, v199, v47, s[62:63]
	v_subrev_u32_e32 v162, 0, v180
	v_subrev_u32_e32 v163, 1, v180
	v_subrev_u32_e32 v164, 2, v180
	v_subrev_u32_e32 v165, 3, v180
	v_subrev_u32_e32 v166, 8, v180
	v_subrev_u32_e32 v167, 9, v180
	v_subrev_u32_e32 v168, 10, v180
	v_subrev_u32_e32 v169, 11, v180
	v_subrev_u32_e32 v170, 16, v180
	v_subrev_u32_e32 v171, 17, v180
	v_subrev_u32_e32 v172, 18, v180
	v_subrev_u32_e32 v173, 19, v180
	v_subrev_u32_e32 v174, 24, v180
	v_subrev_u32_e32 v175, 25, v180
	v_subrev_u32_e32 v176, 26, v180
	v_subrev_u32_e32 v177, 27, v180
	v_med3_i32 v162, v162, 0, v198
	v_med3_i32 v163, v163, 0, v198
	v_med3_i32 v164, v164, 0, v198
	v_med3_i32 v165, v165, 0, v198
	v_med3_i32 v166, v166, 0, v198
	v_med3_i32 v167, v167, 0, v198
	v_med3_i32 v168, v168, 0, v198
	v_med3_i32 v169, v169, 0, v198
	v_med3_i32 v170, v170, 0, v198
	v_med3_i32 v171, v171, 0, v198
	v_med3_i32 v172, v172, 0, v198
	v_med3_i32 v173, v173, 0, v198
	v_med3_i32 v174, v174, 0, v198
	v_med3_i32 v175, v175, 0, v198
	v_med3_i32 v176, v176, 0, v198
	v_med3_i32 v177, v177, 0, v198
	ds_read_u8 v162, v162
	ds_read_u8 v163, v163
	ds_read_u8 v164, v164
	ds_read_u8 v165, v165
	ds_read_u8 v166, v166
	ds_read_u8 v167, v167
	ds_read_u8 v168, v168
	ds_read_u8 v169, v169
	ds_read_u8 v170, v170
	ds_read_u8 v171, v171
	ds_read_u8 v172, v172
	ds_read_u8 v173, v173
	ds_read_u8 v174, v174
	ds_read_u8 v175, v175
	ds_read_u8 v176, v176
	ds_read_u8 v177, v177
	s_waitcnt lgkmcnt(15)
; #define NEGINF (-__builtin_inff())
; DI int crow(int i, int h) { return (i & 3) + 8 * (i >> 2) + 4 * h; }
; DI void moba_item(const Params& p, int b, int hd, int qb, const unsigned char* blut, const float* tbl) {
;     ...
;       if (qb * 32 - (kt * 32 + 31) >= 1513) {
;         const float b31 = tblh[31];
; #pragma unroll
;         for (int i = 0; i < 16; ++i) lg[i] = bs ? s[i] + b31 : NEGINF;
;       } else {
;         int dist[16]; float bv[16];
; #pragma unroll
;         for (int i = 0; i < 16; ++i) dist[i] = t - (kt * 32 + crow(i, h));
;         bias16(blut, tblh, dist, bv);
; #pragma unroll
;         for (int i = 0; i < 16; ++i) lg[i] = (bs && dist[i] >= 0) ? s[i] + bv[i] : NEGINF;
	v_lshl_add_u32 v162, v162, 2, v156
	s_waitcnt lgkmcnt(14)
	v_lshl_add_u32 v163, v163, 2, v156
	s_waitcnt lgkmcnt(13)
	v_lshl_add_u32 v164, v164, 2, v156
	s_waitcnt lgkmcnt(12)
	v_lshl_add_u32 v165, v165, 2, v156
	s_waitcnt lgkmcnt(11)
	v_lshl_add_u32 v166, v166, 2, v156
	s_waitcnt lgkmcnt(10)
	v_lshl_add_u32 v167, v167, 2, v156
	s_waitcnt lgkmcnt(9)
	v_lshl_add_u32 v168, v168, 2, v156
	s_waitcnt lgkmcnt(8)
	v_lshl_add_u32 v169, v169, 2, v156
	s_waitcnt lgkmcnt(7)
	v_lshl_add_u32 v170, v170, 2, v156
	s_waitcnt lgkmcnt(6)
	v_lshl_add_u32 v171, v171, 2, v156
	s_waitcnt lgkmcnt(5)
	v_lshl_add_u32 v172, v172, 2, v156
	s_waitcnt lgkmcnt(4)
	v_lshl_add_u32 v173, v173, 2, v156
	s_waitcnt lgkmcnt(3)
	v_lshl_add_u32 v174, v174, 2, v156
	s_waitcnt lgkmcnt(2)
	v_lshl_add_u32 v175, v175, 2, v156
	s_waitcnt lgkmcnt(1)
	v_lshl_add_u32 v176, v176, 2, v156
	s_waitcnt lgkmcnt(0)
	v_lshl_add_u32 v177, v177, 2, v156
	ds_read_b32 v162, v162 offset:4864
	ds_read_b32 v163, v163 offset:4864
	ds_read_b32 v164, v164 offset:4864
	ds_read_b32 v165, v165 offset:4864
	ds_read_b32 v166, v166 offset:4864
	ds_read_b32 v167, v167 offset:4864
	ds_read_b32 v168, v168 offset:4864
	ds_read_b32 v169, v169 offset:4864
	ds_read_b32 v170, v170 offset:4864
	ds_read_b32 v171, v171 offset:4864
	ds_read_b32 v172, v172 offset:4864
	ds_read_b32 v173, v173 offset:4864
	ds_read_b32 v174, v174 offset:4864
	ds_read_b32 v175, v175 offset:4864
	ds_read_b32 v176, v176 offset:4864
	ds_read_b32 v177, v177 offset:4864
	s_waitcnt lgkmcnt(15)
	v_add_f32_e32 v48, v48, v162
	v_cndmask_b32_e64 v48, v199, v48, s[62:63]
	s_waitcnt lgkmcnt(14)
	v_add_f32_e32 v49, v49, v163
	v_cndmask_b32_e64 v49, v199, v49, s[62:63]
	s_waitcnt lgkmcnt(13)
	v_add_f32_e32 v50, v50, v164
	v_cndmask_b32_e64 v50, v199, v50, s[62:63]
	s_waitcnt lgkmcnt(12)
	v_add_f32_e32 v51, v51, v165
	v_cndmask_b32_e64 v51, v199, v51, s[62:63]
	s_waitcnt lgkmcnt(11)
	v_add_f32_e32 v52, v52, v166
	v_cndmask_b32_e64 v52, v199, v52, s[62:63]
	s_waitcnt lgkmcnt(10)
	v_add_f32_e32 v53, v53, v167
	v_cndmask_b32_e64 v53, v199, v53, s[62:63]
	s_waitcnt lgkmcnt(9)
	v_add_f32_e32 v54, v54, v168
	v_cndmask_b32_e64 v54, v199, v54, s[62:63]
	s_waitcnt lgkmcnt(8)
	v_add_f32_e32 v55, v55, v169
	v_cndmask_b32_e64 v55, v199, v55, s[62:63]
	s_waitcnt lgkmcnt(7)
	v_add_f32_e32 v56, v56, v170
	v_cndmask_b32_e64 v56, v199, v56, s[62:63]
	s_waitcnt lgkmcnt(6)
	v_add_f32_e32 v57, v57, v171
	v_cndmask_b32_e64 v57, v199, v57, s[62:63]
	s_waitcnt lgkmcnt(5)
	v_add_f32_e32 v58, v58, v172
	v_cndmask_b32_e64 v58, v199, v58, s[62:63]
	s_waitcnt lgkmcnt(4)
	v_add_f32_e32 v59, v59, v173
	v_cndmask_b32_e64 v59, v199, v59, s[62:63]
	s_waitcnt lgkmcnt(3)
	v_add_f32_e32 v60, v60, v174
	v_cndmask_b32_e64 v60, v199, v60, s[62:63]
	s_waitcnt lgkmcnt(2)
	v_add_f32_e32 v61, v61, v175
	v_cndmask_b32_e64 v61, v199, v61, s[62:63]
	s_waitcnt lgkmcnt(1)
	v_add_f32_e32 v62, v62, v176
	v_cndmask_b32_e64 v62, v199, v62, s[62:63]
	s_waitcnt lgkmcnt(0)
	v_add_f32_e32 v63, v63, v177
	v_cndmask_b32_e64 v63, v199, v63, s[62:63]
	s_branch .Lamoba_softmax
.Lamoba_far:
	s_nop 7
	v_add_f32_e32 v32, v32, v178
	v_add_f32_e32 v33, v33, v178
	v_add_f32_e32 v34, v34, v178
	v_add_f32_e32 v35, v35, v178
	v_add_f32_e32 v36, v36, v178
	v_add_f32_e32 v37, v37, v178
	v_add_f32_e32 v38, v38, v178
	v_add_f32_e32 v39, v39, v178
	v_add_f32_e32 v40, v40, v178
	v_add_f32_e32 v41, v41, v178
	v_add_f32_e32 v42, v42, v178
	v_add_f32_e32 v43, v43, v178
	v_add_f32_e32 v44, v44, v178
	v_add_f32_e32 v45, v45, v178
	v_add_f32_e32 v46, v46, v178
	v_add_f32_e32 v47, v47, v178
	v_add_f32_e32 v48, v48, v178
	v_add_f32_e32 v49, v49, v178
	v_add_f32_e32 v50, v50, v178
	v_add_f32_e32 v51, v51, v178
	v_add_f32_e32 v52, v52, v178
	v_add_f32_e32 v53, v53, v178
	v_add_f32_e32 v54, v54, v178
	v_add_f32_e32 v55, v55, v178
	v_add_f32_e32 v56, v56, v178
	v_add_f32_e32 v57, v57, v178
	v_add_f32_e32 v58, v58, v178
	v_add_f32_e32 v59, v59, v178
	v_add_f32_e32 v60, v60, v178
	v_add_f32_e32 v61, v61, v178
	v_add_f32_e32 v62, v62, v178
	v_add_f32_e32 v63, v63, v178
	v_cndmask_b32_e64 v32, v199, v32, s[62:63]
	v_cndmask_b32_e64 v33, v199, v33, s[62:63]
	v_cndmask_b32_e64 v34, v199, v34, s[62:63]
	v_cndmask_b32_e64 v35, v199, v35, s[62:63]
	v_cndmask_b32_e64 v36, v199, v36, s[62:63]
	v_cndmask_b32_e64 v37, v199, v37, s[62:63]
	v_cndmask_b32_e64 v38, v199, v38, s[62:63]
	v_cndmask_b32_e64 v39, v199, v39, s[62:63]
	v_cndmask_b32_e64 v40, v199, v40, s[62:63]
	v_cndmask_b32_e64 v41, v199, v41, s[62:63]
	v_cndmask_b32_e64 v42, v199, v42, s[62:63]
	v_cndmask_b32_e64 v43, v199, v43, s[62:63]
	v_cndmask_b32_e64 v44, v199, v44, s[62:63]
	v_cndmask_b32_e64 v45, v199, v45, s[62:63]
	v_cndmask_b32_e64 v46, v199, v46, s[62:63]
	v_cndmask_b32_e64 v47, v199, v47, s[62:63]
	v_cndmask_b32_e64 v48, v199, v48, s[62:63]
	v_cndmask_b32_e64 v49, v199, v49, s[62:63]
	v_cndmask_b32_e64 v50, v199, v50, s[62:63]
	v_cndmask_b32_e64 v51, v199, v51, s[62:63]
	v_cndmask_b32_e64 v52, v199, v52, s[62:63]
	v_cndmask_b32_e64 v53, v199, v53, s[62:63]
	v_cndmask_b32_e64 v54, v199, v54, s[62:63]
	v_cndmask_b32_e64 v55, v199, v55, s[62:63]
	v_cndmask_b32_e64 v56, v199, v56, s[62:63]
	v_cndmask_b32_e64 v57, v199, v57, s[62:63]
	v_cndmask_b32_e64 v58, v199, v58, s[62:63]
	v_cndmask_b32_e64 v59, v199, v59, s[62:63]
	v_cndmask_b32_e64 v60, v199, v60, s[62:63]
	v_cndmask_b32_e64 v61, v199, v61, s[62:63]
	v_cndmask_b32_e64 v62, v199, v62, s[62:63]
	v_cndmask_b32_e64 v63, v199, v63, s[62:63]
; #define MFMA32(a, b, c) __builtin_amdgcn_mfma_f32_32x32x16_bf16((a), (b), (c), 0, 0, 0)
; #define NEGINF (-__builtin_inff())
; DI float shx32(float v) { const auto r = __builtin_amdgcn_permlane32_swap(__float_as_uint(v), __float_as_uint(v), false, false); return __uint_as_float((threadIdx.x & 32) ? r[0] : r[1]); }
; DI float ex2(float x) { return __builtin_amdgcn_exp2f(x); }
; DI unsigned pack2(float a, float b) { unsigned r; asm("v_cvt_pk_bf16_f32 %0, %1, %2" : "=v"(r) : "v"(a), "v"(b)); return r; }
; DI void softmax_step_r(AttnSt& st, const float (&lg)[16], const KVT& t) {
;   float mx = NEGINF;
; #pragma unroll
;   for (int i = 0; i < 16; ++i) mx = fmaxf(mx, lg[i]);
;   mx = fmaxf(mx, shx32(mx));
;   if (__ballot(mx > NEGINF) == 0ull) return;
;   const float mnew = fmaxf(st.m, mx);
;   const float muse = (mnew == NEGINF) ? 0.f : mnew;
;   const float alpha = ex2(st.m - muse);
;   float pr[16]; float rs = 0.f;
; #pragma unroll
;   for (int i = 0; i < 16; ++i) { pr[i] = ex2(lg[i] - muse); rs += pr[i]; }
;   st.l = st.l * alpha + rs;
;   if (__ballot(mnew != st.m) != 0ull) {
; #pragma unroll
;     for (int i = 0; i < 16; ++i) { st.o0[i] *= alpha; st.o1[i] *= alpha; }
;   }
;   st.m = mnew;
; #pragma unroll
;   for (int s2 = 0; s2 < 2; ++s2) {
;     u32x4 pk; pk.x = pack2(pr[8 * s2], pr[8 * s2 + 1]); pk.y = pack2(pr[8 * s2 + 2], pr[8 * s2 + 3]); pk.z = pack2(pr[8 * s2 + 4], pr[8 * s2 + 5]); pk.w = pack2(pr[8 * s2 + 6], pr[8 * s2 + 7]);
;     const bf16x8 pb = __builtin_bit_cast(bf16x8, pk);
;     const bf16x8 va0 = __builtin_shufflevector(t.v[s2 * 4 + 0], t.v[s2 * 4 + 1], 0, 1, 2, 3, 4, 5, 6, 7);
;     st.o0 = MFMA32(va0, pb, st.o0);
;     const bf16x8 va1 = __builtin_shufflevector(t.v[s2 * 4 + 2], t.v[s2 * 4 + 3], 0, 1, 2, 3, 4, 5, 6, 7);
;     st.o1 = MFMA32(va1, pb, st.o1);
;   }
; }
; template <class KP, class VP, class ACT, class FILL>
; DI void attn_loop(AttnSt& st, const bf16x8 (&qf)[4], int k0, int k1, size_t vstride, KP kp, VP vp, ACT act, FILL fill) {
;     ...
;     {
;       const bf16_t* v0 = vp(kn);
; #pragma unroll
;       for (int j = 0; j < 8; ++j) nxt.v[j] = *(const s16x4*)(v0 + 256 * j);
;     }
.Lamoba_softmax:
	v_max3_f32 v162, v32, v33, v34
	v_max3_f32 v163, v40, v41, v42
	v_max3_f32 v164, v48, v49, v50
	v_max3_f32 v165, v56, v57, v58
	v_max3_f32 v162, v162, v35, v36
	v_max3_f32 v163, v163, v43, v44
	v_max3_f32 v164, v164, v51, v52
	v_max3_f32 v165, v165, v59, v60
	v_max3_f32 v162, v162, v37, v38
	v_max3_f32 v163, v163, v45, v46
	v_max3_f32 v164, v164, v53, v54
	v_max3_f32 v165, v165, v61, v62
	v_max_f32_e32 v162, v162, v39
	v_max_f32_e32 v163, v163, v47
	v_max_f32_e32 v164, v164, v55
	v_max_f32_e32 v165, v165, v63
	v_max3_f32 v162, v162, v163, v164
	v_max_f32_e32 v162, v162, v165
	v_mov_b32_e32 v163, v162
	v_mov_b32_e32 v164, v162
	s_nop 1
	v_permlane32_swap_b32_e32 v163, v164
	v_cndmask_b32_e64 v163, v163, v164, s[12:13]
	v_max_f32_e32 v162, v162, v163
	v_max_f32_e32 v163, v161, v162
	v_cmp_neq_f32_e32 vcc, v199, v163
	s_nop 1
	v_cndmask_b32_e32 v164, 0, v163, vcc
	v_sub_f32_e32 v165, v161, v164
	v_exp_f32_e32 v165, v165
	v_mov_b32_e32 v161, v163
	v_sub_f32_e32 v32, v32, v164
	v_sub_f32_e32 v33, v33, v164
	v_sub_f32_e32 v34, v34, v164
	v_sub_f32_e32 v35, v35, v164
	v_sub_f32_e32 v36, v36, v164
	v_sub_f32_e32 v37, v37, v164
	v_sub_f32_e32 v38, v38, v164
	v_sub_f32_e32 v39, v39, v164
	v_sub_f32_e32 v40, v40, v164
	v_sub_f32_e32 v41, v41, v164
	v_sub_f32_e32 v42, v42, v164
	v_sub_f32_e32 v43, v43, v164
	v_sub_f32_e32 v44, v44, v164
	v_sub_f32_e32 v45, v45, v164
	v_sub_f32_e32 v46, v46, v164
	v_sub_f32_e32 v47, v47, v164
	v_sub_f32_e32 v48, v48, v164
	v_sub_f32_e32 v49, v49, v164
	v_sub_f32_e32 v50, v50, v164
	v_sub_f32_e32 v51, v51, v164
	v_sub_f32_e32 v52, v52, v164
	v_sub_f32_e32 v53, v53, v164
	v_sub_f32_e32 v54, v54, v164
	v_sub_f32_e32 v55, v55, v164
	v_sub_f32_e32 v56, v56, v164
	v_sub_f32_e32 v57, v57, v164
	v_sub_f32_e32 v58, v58, v164
	v_sub_f32_e32 v59, v59, v164
	v_sub_f32_e32 v60, v60, v164
	v_sub_f32_e32 v61, v61, v164
	v_sub_f32_e32 v62, v62, v164
	v_sub_f32_e32 v63, v63, v164
	v_exp_f32_e32 v32, v32
	v_exp_f32_e32 v33, v33
	v_exp_f32_e32 v34, v34
	v_exp_f32_e32 v35, v35
	v_exp_f32_e32 v36, v36
	v_exp_f32_e32 v37, v37
	v_exp_f32_e32 v38, v38
	v_exp_f32_e32 v39, v39
	v_exp_f32_e32 v40, v40
	v_exp_f32_e32 v41, v41
	v_exp_f32_e32 v42, v42
	v_exp_f32_e32 v43, v43
	v_exp_f32_e32 v44, v44
	v_exp_f32_e32 v45, v45
	v_exp_f32_e32 v46, v46
	v_exp_f32_e32 v47, v47
	v_exp_f32_e32 v48, v48
	v_exp_f32_e32 v49, v49
	v_exp_f32_e32 v50, v50
	v_exp_f32_e32 v51, v51
	v_exp_f32_e32 v52, v52
	v_exp_f32_e32 v53, v53
	v_exp_f32_e32 v54, v54
	v_exp_f32_e32 v55, v55
	v_exp_f32_e32 v56, v56
	v_exp_f32_e32 v57, v57
	v_exp_f32_e32 v58, v58
	v_exp_f32_e32 v59, v59
	v_exp_f32_e32 v60, v60
	v_exp_f32_e32 v61, v61
	v_exp_f32_e32 v62, v62
	v_exp_f32_e32 v63, v63
	v_add_f32_e32 v166, v32, v33
	v_add_f32_e32 v167, v40, v41
	v_add_f32_e32 v168, v48, v49
	v_add_f32_e32 v169, v56, v57
	v_add_f32_e32 v166, v166, v34
	v_add_f32_e32 v167, v167, v42
	v_add_f32_e32 v168, v168, v50
	v_add_f32_e32 v169, v169, v58
	v_add_f32_e32 v166, v166, v35
	v_add_f32_e32 v167, v167, v43
	v_add_f32_e32 v168, v168, v51
	v_add_f32_e32 v169, v169, v59
	v_add_f32_e32 v166, v166, v36
	v_add_f32_e32 v167, v167, v44
	v_add_f32_e32 v168, v168, v52
	v_add_f32_e32 v169, v169, v60
	v_add_f32_e32 v166, v166, v37
	v_add_f32_e32 v167, v167, v45
	v_add_f32_e32 v168, v168, v53
	v_add_f32_e32 v169, v169, v61
	v_add_f32_e32 v166, v166, v38
	v_add_f32_e32 v167, v167, v46
	v_add_f32_e32 v168, v168, v54
	v_add_f32_e32 v169, v169, v62
	v_add_f32_e32 v166, v166, v39
	v_add_f32_e32 v167, v167, v47
	v_add_f32_e32 v168, v168, v55
	v_add_f32_e32 v169, v169, v63
	v_add_f32_e32 v166, v166, v167
	v_add_f32_e32 v168, v168, v169
	v_add_f32_e32 v166, v166, v168
	v_fma_f32 v160, v160, v165, v166
	v_mul_f32_e32 v0, v165, v0
	v_mul_f32_e32 v1, v165, v1
	v_mul_f32_e32 v2, v165, v2
	v_mul_f32_e32 v3, v165, v3
	v_mul_f32_e32 v4, v165, v4
	v_mul_f32_e32 v5, v165, v5
	v_mul_f32_e32 v6, v165, v6
	v_mul_f32_e32 v7, v165, v7
	v_mul_f32_e32 v8, v165, v8
	v_mul_f32_e32 v9, v165, v9
	v_mul_f32_e32 v10, v165, v10
	v_mul_f32_e32 v11, v165, v11
	v_mul_f32_e32 v12, v165, v12
	v_mul_f32_e32 v13, v165, v13
	v_mul_f32_e32 v14, v165, v14
	v_mul_f32_e32 v15, v165, v15
	v_mul_f32_e32 v16, v165, v16
	v_mul_f32_e32 v17, v165, v17
	v_mul_f32_e32 v18, v165, v18
	v_mul_f32_e32 v19, v165, v19
	v_mul_f32_e32 v20, v165, v20
	v_mul_f32_e32 v21, v165, v21
	v_mul_f32_e32 v22, v165, v22
	v_mul_f32_e32 v23, v165, v23
	v_mul_f32_e32 v24, v165, v24
	v_mul_f32_e32 v25, v165, v25
	v_mul_f32_e32 v26, v165, v26
	v_mul_f32_e32 v27, v165, v27
	v_mul_f32_e32 v28, v165, v28
	v_mul_f32_e32 v29, v165, v29
	v_mul_f32_e32 v30, v165, v30
	v_mul_f32_e32 v31, v165, v31
	v_cvt_pk_bf16_f32 v162, v32, v33
	v_cvt_pk_bf16_f32 v163, v34, v35
	v_cvt_pk_bf16_f32 v164, v36, v37
	v_cvt_pk_bf16_f32 v165, v38, v39
	v_cvt_pk_bf16_f32 v166, v40, v41
	v_cvt_pk_bf16_f32 v167, v42, v43
	v_cvt_pk_bf16_f32 v168, v44, v45
	v_cvt_pk_bf16_f32 v169, v46, v47
	v_cvt_pk_bf16_f32 v170, v48, v49
	v_cvt_pk_bf16_f32 v171, v50, v51
	v_cvt_pk_bf16_f32 v172, v52, v53
	v_cvt_pk_bf16_f32 v173, v54, v55
	v_cvt_pk_bf16_f32 v174, v56, v57
	v_cvt_pk_bf16_f32 v175, v58, v59
	v_cvt_pk_bf16_f32 v176, v60, v61
	v_cvt_pk_bf16_f32 v177, v62, v63
	s_waitcnt vmcnt(8)
	s_nop 1
	v_mfma_f32_32x32x16_bf16 v[0:15], v[64:67], v[162:165], v[0:15]
	v_mfma_f32_32x32x16_bf16 v[16:31], v[68:71], v[162:165], v[16:31]
	v_mfma_f32_32x32x16_bf16 v[0:15], v[72:75], v[166:169], v[0:15]
	v_mfma_f32_32x32x16_bf16 v[16:31], v[76:79], v[166:169], v[16:31]
	v_mfma_f32_32x32x16_bf16 v[0:15], v[138:141], v[170:173], v[0:15]
	v_mfma_f32_32x32x16_bf16 v[16:31], v[142:145], v[170:173], v[16:31]
	v_mfma_f32_32x32x16_bf16 v[0:15], v[146:149], v[174:177], v[0:15]
	v_mfma_f32_32x32x16_bf16 v[16:31], v[150:153], v[174:177], v[16:31]
	s_add_u32 s23, s56, 2
	s_min_u32 s24, s23, s60
	s_lshl_b32 s26, s24, 12
	s_mov_b32 s27, 0
	v_lshl_add_u64 v[218:219], v[136:137], 0, s[26:27]
	global_load_dwordx2 v[64:65], v[218:219], off
	global_load_dwordx2 v[66:67], v[218:219], off offset:512
	global_load_dwordx2 v[68:69], v[218:219], off offset:1024
	global_load_dwordx2 v[70:71], v[218:219], off offset:1536
	global_load_dwordx2 v[72:73], v[218:219], off offset:2048
	global_load_dwordx2 v[74:75], v[218:219], off offset:2560
	global_load_dwordx2 v[76:77], v[218:219], off offset:3072
	global_load_dwordx2 v[78:79], v[218:219], off offset:3584
	s_add_u32 s23, s56, 3
	s_min_u32 s24, s23, s60
	s_lshl_b32 s26, s24, 12
	s_mov_b32 s27, 0
	v_lshl_add_u64 v[218:219], v[136:137], 0, s[26:27]
	global_load_dwordx2 v[138:139], v[218:219], off
	global_load_dwordx2 v[140:141], v[218:219], off offset:512
	global_load_dwordx2 v[142:143], v[218:219], off offset:1024
	global_load_dwordx2 v[144:145], v[218:219], off offset:1536
	global_load_dwordx2 v[146:147], v[218:219], off offset:2048
	global_load_dwordx2 v[148:149], v[218:219], off offset:2560
	global_load_dwordx2 v[150:151], v[218:219], off offset:3072
	global_load_dwordx2 v[152:153], v[218:219], off offset:3584
	s_add_u32 s56, s56, 2
	s_cmp_le_u32 s56, s60
	s_cbranch_scc1 .Lamoba_loop
; template <class KP, class VP, class ACT, class FILL>
; DI void attn_loop(AttnSt& st, const bf16x8 (&qf)[4], int k0, int k1, size_t vstride, KP kp, VP vp, ACT act, FILL fill) {
;     ...
;     if (act(kt)) {
;       float lg[16];
;       fill(kt, s_cur, lg);
;       softmax_step_r(st, lg, cur);
;     }
;     s_cur = s_next;
; #pragma unroll
;     for (int i = 0; i < 8; ++i) cur.v[i] = nxt.v[i];
; #pragma unroll
;     for (int ss = 0; ss < 4; ++ss) nxt.k[ss] = k2[ss];
;   }
	s_nop 15
	s_waitcnt vmcnt(0)
	s_mov_b64 s[58:59], 0
	s_branch .LBB0_933
